# fox_attn epilogue: o_norm gain vector loaded once into v[64:71] instead of re-loaded behind each row-group store (3 fewer store-ack+load round trips per fox unit)
# speedup vs baseline: 1.0045x; 1.0045x over previous
.LBB0_161:
	s_or_b64 exec, exec, s[20:21]
	ds_bpermute_b32 v0, v187, v202
	s_lshl_b64 s[2:3], s[34:35], 2
	s_add_u32 s2, s48, s2
	s_mulk_i32 s54, 0x1200
	s_addc_u32 s3, s49, s3
	s_waitcnt lgkmcnt(0)
	v_add_f32_e32 v0, v202, v0
	v_div_scale_f32 v2, s[6:7], v0, v0, 1.0
	v_rcp_f32_e32 v3, v2
	s_add_i32 s6, s54, 0
	s_barrier
	v_fma_f32 v4, -v2, v3, 1.0
	v_fmac_f32_e32 v3, v4, v3
	v_div_scale_f32 v4, vcc, 1.0, v0, 1.0
	v_mul_f32_e32 v5, v4, v3
	v_fma_f32 v6, -v2, v5, v4
	v_fmac_f32_e32 v5, v6, v3
	v_fma_f32 v2, -v2, v5, v4
	v_div_fmas_f32 v2, v2, v3, v5
	v_div_fixup_f32 v0, v2, v0, 1.0
	v_pk_mul_f32 v[2:3], v[34:35], v[0:1] op_sel_hi:[1,0]
	v_pk_mul_f32 v[4:5], v[18:19], v[0:1] op_sel_hi:[1,0]
	v_pk_mul_f32 v[6:7], v[36:37], v[0:1] op_sel_hi:[1,0]
	v_pk_mul_f32 v[8:9], v[20:21], v[0:1] op_sel_hi:[1,0]
	v_pk_mul_f32 v[10:11], v[38:39], v[0:1] op_sel_hi:[1,0]
	v_pk_mul_f32 v[12:13], v[22:23], v[0:1] op_sel_hi:[1,0]
	v_pk_mul_f32 v[14:15], v[40:41], v[0:1] op_sel_hi:[1,0]
	v_pk_mul_f32 v[16:17], v[24:25], v[0:1] op_sel_hi:[1,0]
	v_pk_mul_f32 v[18:19], v[42:43], v[0:1] op_sel_hi:[1,0]
	v_pk_mul_f32 v[20:21], v[26:27], v[0:1] op_sel_hi:[1,0]
	v_pk_mul_f32 v[22:23], v[44:45], v[0:1] op_sel_hi:[1,0]
	v_pk_mul_f32 v[24:25], v[28:29], v[0:1] op_sel_hi:[1,0]
	v_pk_mul_f32 v[26:27], v[46:47], v[0:1] op_sel_hi:[1,0]
	v_pk_mul_f32 v[28:29], v[30:31], v[0:1] op_sel_hi:[1,0]
	v_pk_mul_f32 v[30:31], v[48:49], v[0:1] op_sel_hi:[1,0]
	v_pk_mul_f32 v[32:33], v[32:33], v[0:1] op_sel_hi:[1,0]
	v_mul_u32_u24_e32 v0, 0x90, v188
	v_add3_u32 v0, s6, v0, v191
	v_cvt_pk_bf16_f32 v2, v2, v3
	v_cvt_pk_bf16_f32 v3, v6, v7
	v_cvt_pk_bf16_f32 v6, v10, v11
	v_cvt_pk_bf16_f32 v7, v14, v15
	v_add_u32_e32 v0, 0x8000, v0
	ds_write2_b64 v0, v[2:3], v[6:7] offset1:2
	v_cvt_pk_bf16_f32 v2, v18, v19
	v_cvt_pk_bf16_f32 v3, v22, v23
	v_cvt_pk_bf16_f32 v6, v26, v27
	v_cvt_pk_bf16_f32 v7, v30, v31
	ds_write2_b64 v0, v[2:3], v[6:7] offset0:4 offset1:6
	v_cvt_pk_bf16_f32 v2, v4, v5
	v_cvt_pk_bf16_f32 v3, v8, v9
	v_cvt_pk_bf16_f32 v4, v12, v13
	v_cvt_pk_bf16_f32 v5, v16, v17
	ds_write2_b64 v0, v[2:3], v[4:5] offset0:8 offset1:10
	v_cvt_pk_bf16_f32 v2, v20, v21
	v_cvt_pk_bf16_f32 v3, v24, v25
	v_cvt_pk_bf16_f32 v4, v28, v29
	v_cvt_pk_bf16_f32 v5, v32, v33
	ds_write2_b64 v0, v[2:3], v[4:5] offset0:12 offset1:14
	v_lshlrev_b32_e32 v0, 3, v185
	v_lshrrev_b32_e32 v15, 3, v185
	v_and_b32_e32 v2, 56, v0
	s_lshl_b32 s7, s57, 2
	v_lshlrev_b32_e32 v0, 1, v2
	s_add_u32 s20, s2, s7
	v_lshlrev_b32_e32 v22, 2, v2
	v_mul_u32_u24_e32 v2, 0x90, v15
	s_waitcnt lgkmcnt(0)
	s_addc_u32 s21, s3, 0
	v_add3_u32 v14, s6, v0, v2
	ds_read_b128 v[2:5], v14 offset:32768
	global_load_dwordx4 v[64:67], v22, s[20:21]
	global_load_dwordx4 v[68:71], v22, s[20:21] offset:16
	ds_read_b128 v[10:13], v14 offset:33920
	s_mov_b32 s2, 0x358637bd
	s_waitcnt lgkmcnt(0)
	v_lshlrev_b32_e32 v32, 16, v2
	v_and_b32_e32 v33, 0xffff0000, v2
	v_lshlrev_b32_e32 v44, 16, v10
	v_and_b32_e32 v45, 0xffff0000, v10
	v_lshlrev_b32_e32 v28, 16, v3
	v_and_b32_e32 v29, 0xffff0000, v3
	v_pk_mul_f32 v[2:3], v[32:33], v[32:33]
	v_lshlrev_b32_e32 v40, 16, v11
	v_and_b32_e32 v41, 0xffff0000, v11
	v_pk_mul_f32 v[10:11], v[44:45], v[44:45]
	v_pk_mul_f32 v[30:31], v[28:29], v[28:29]
	v_pk_mul_f32 v[42:43], v[40:41], v[40:41]
	v_mov_b32_e32 v46, v10
	v_mov_b32_e32 v47, v2
	v_mov_b32_e32 v2, v11
	v_lshlrev_b32_e32 v26, 16, v4
	v_and_b32_e32 v27, 0xffff0000, v4
	v_lshlrev_b32_e32 v38, 16, v12
	v_and_b32_e32 v39, 0xffff0000, v12
	v_pk_add_f32 v[2:3], v[46:47], v[2:3]
	v_mov_b32_e32 v10, v42
	v_mov_b32_e32 v11, v30
	v_lshlrev_b32_e32 v20, 16, v5
	v_and_b32_e32 v21, 0xffff0000, v5
	v_pk_mul_f32 v[4:5], v[26:27], v[26:27]
	v_lshlrev_b32_e32 v34, 16, v13
	v_and_b32_e32 v35, 0xffff0000, v13
	v_pk_mul_f32 v[12:13], v[38:39], v[38:39]
	v_pk_add_f32 v[2:3], v[10:11], v[2:3]
	v_mov_b32_e32 v30, v43
	v_pk_add_f32 v[2:3], v[30:31], v[2:3]
	v_mov_b32_e32 v10, v12
	v_mov_b32_e32 v11, v4
	v_pk_mul_f32 v[24:25], v[20:21], v[20:21]
	v_pk_mul_f32 v[36:37], v[34:35], v[34:35]
	v_pk_add_f32 v[2:3], v[10:11], v[2:3]
	v_mov_b32_e32 v4, v13
	v_pk_add_f32 v[2:3], v[4:5], v[2:3]
	v_mov_b32_e32 v4, v36
	v_mov_b32_e32 v5, v24
	v_pk_add_f32 v[2:3], v[4:5], v[2:3]
	v_mov_b32_e32 v24, v37
	v_pk_add_f32 v[2:3], v[24:25], v[2:3]
	ds_bpermute_b32 v5, v147, v3
	ds_bpermute_b32 v4, v147, v2
	v_mov_b64_e32 v[12:13], s[2:3]
	s_mov_b32 s2, 0x3c800000
	v_or_b32_e32 v10, s55, v15
	v_mov_b32_e32 v11, s56
	s_waitcnt lgkmcnt(0)
	v_pk_add_f32 v[2:3], v[2:3], v[4:5]
	ds_bpermute_b32 v5, v159, v3
	ds_bpermute_b32 v4, v159, v2
	v_lshlrev_b64 v[24:25], 11, v[10:11]
	s_waitcnt lgkmcnt(0)
	v_pk_add_f32 v[2:3], v[2:3], v[4:5]
	ds_bpermute_b32 v5, v184, v3
	ds_bpermute_b32 v4, v184, v2
	s_waitcnt lgkmcnt(0)
	v_pk_add_f32 v[2:3], v[2:3], v[4:5]
	s_nop 0
	v_pk_fma_f32 v[30:31], v[2:3], s[2:3], v[12:13] op_sel_hi:[1,0,0]
	s_nop 0
	v_mul_f32_e32 v2, 0x4b800000, v31
	v_cmp_gt_f32_e32 vcc, s96, v31
	v_mul_f32_e32 v15, 0x4b800000, v30
	s_nop 0
	v_cndmask_b32_e32 v2, v31, v2, vcc
	v_rsq_f32_e32 v4, v2
	v_lshl_add_u64 v[2:3], s[74:75], 0, v[24:25]
	v_lshl_add_u64 v[2:3], v[2:3], 0, s[80:81]
	v_lshl_add_u64 v[24:25], v[2:3], 0, v[0:1]
	v_mul_f32_e32 v2, 0x45800000, v4
	v_cndmask_b32_e32 v2, v4, v2, vcc
	v_pk_mul_f32 v[4:5], v[2:3], v[32:33] op_sel_hi:[0,1]
	s_waitcnt vmcnt(0)
	v_pk_mul_f32 v[4:5], v[64:65], v[4:5]
	v_pk_mul_f32 v[6:7], v[2:3], v[28:29] op_sel_hi:[0,1]
	v_pk_mul_f32 v[6:7], v[66:67], v[6:7]
	v_pk_mul_f32 v[8:9], v[2:3], v[26:27] op_sel_hi:[0,1]
	v_pk_mul_f32 v[2:3], v[2:3], v[20:21] op_sel_hi:[0,1]
	v_pk_mul_f32 v[8:9], v[68:69], v[8:9]
	v_pk_mul_f32 v[16:17], v[70:71], v[2:3]
	v_cvt_pk_bf16_f32 v2, v4, v5
	v_cvt_pk_bf16_f32 v3, v6, v7
	v_cvt_pk_bf16_f32 v4, v8, v9
	v_cvt_pk_bf16_f32 v5, v16, v17
	global_store_dwordx4 v[24:25], v[2:5], off offset:512
	s_nop 0
	v_cmp_gt_f32_e32 vcc, s96, v30
	v_mov_b32_e32 v17, s56
	v_or_b32_e32 v16, 8, v10
	v_cndmask_b32_e32 v15, v30, v15, vcc
	v_rsq_f32_e32 v15, v15
	v_lshlrev_b64 v[16:17], 11, v[16:17]
	v_lshl_add_u64 v[16:17], s[74:75], 0, v[16:17]
	v_lshl_add_u64 v[16:17], v[16:17], 0, s[80:81]
	v_mul_f32_e32 v23, 0x45800000, v15
	v_cndmask_b32_e32 v24, v15, v23, vcc
	v_pk_mul_f32 v[26:27], v[24:25], v[44:45] op_sel_hi:[0,1]
	v_pk_mul_f32 v[28:29], v[24:25], v[40:41] op_sel_hi:[0,1]
	v_pk_mul_f32 v[30:31], v[24:25], v[38:39] op_sel_hi:[0,1]
	v_pk_mul_f32 v[24:25], v[24:25], v[34:35] op_sel_hi:[0,1]
	v_lshl_add_u64 v[20:21], v[16:17], 0, v[0:1]
	ds_read_b128 v[16:19], v14 offset:35072
	s_waitcnt lgkmcnt(0)
	v_lshlrev_b32_e32 v34, 16, v16
	v_and_b32_e32 v35, 0xffff0000, v16
	v_lshlrev_b32_e32 v32, 16, v17
	v_and_b32_e32 v33, 0xffff0000, v17
	v_pk_mul_f32 v[38:39], v[34:35], v[34:35]
	v_pk_mul_f32 v[36:37], v[32:33], v[32:33]
	v_mov_b32_e32 v49, v38
	v_pk_mul_f32 v[2:3], v[64:65], v[26:27]
	v_pk_mul_f32 v[4:5], v[66:67], v[28:29]
	v_pk_mul_f32 v[6:7], v[68:69], v[30:31]
	v_pk_mul_f32 v[8:9], v[70:71], v[24:25]
	v_cvt_pk_bf16_f32 v2, v2, v3
	v_cvt_pk_bf16_f32 v3, v4, v5
	v_cvt_pk_bf16_f32 v4, v6, v7
	v_cvt_pk_bf16_f32 v5, v8, v9
	global_store_dwordx4 v[20:21], v[2:5], off offset:512
	s_nop 0
	ds_read_b128 v[24:27], v14 offset:36224
	v_lshlrev_b32_e32 v28, 16, v19
	v_and_b32_e32 v29, 0xffff0000, v19
	v_lshlrev_b32_e32 v30, 16, v18
	v_and_b32_e32 v31, 0xffff0000, v18
	s_waitcnt lgkmcnt(0)
	v_lshlrev_b32_e32 v20, 16, v24
	v_and_b32_e32 v21, 0xffff0000, v24
	v_lshlrev_b32_e32 v18, 16, v25
	v_and_b32_e32 v19, 0xffff0000, v25
	v_pk_mul_f32 v[46:47], v[20:21], v[20:21]
	v_pk_mul_f32 v[44:45], v[18:19], v[18:19]
	v_mov_b32_e32 v48, v46
	v_mov_b32_e32 v38, v47
	v_lshlrev_b32_e32 v16, 16, v26
	v_and_b32_e32 v17, 0xffff0000, v26
	v_mov_b32_e32 v46, v44
	v_mov_b32_e32 v47, v36
	v_pk_add_f32 v[38:39], v[48:49], v[38:39]
	v_lshlrev_b32_e32 v14, 16, v27
	v_and_b32_e32 v15, 0xffff0000, v27
	v_pk_mul_f32 v[26:27], v[30:31], v[30:31]
	v_pk_mul_f32 v[42:43], v[16:17], v[16:17]
	v_mov_b32_e32 v36, v45
	v_pk_add_f32 v[38:39], v[46:47], v[38:39]
	v_mov_b32_e32 v44, v42
	v_mov_b32_e32 v45, v26
	v_pk_add_f32 v[36:37], v[36:37], v[38:39]
	v_pk_mul_f32 v[24:25], v[28:29], v[28:29]
	v_pk_mul_f32 v[40:41], v[14:15], v[14:15]
	v_mov_b32_e32 v26, v43
	v_pk_add_f32 v[36:37], v[44:45], v[36:37]
	v_mov_b32_e32 v42, v40
	v_mov_b32_e32 v43, v24
	v_pk_add_f32 v[26:27], v[26:27], v[36:37]
	v_mov_b32_e32 v24, v41
	v_pk_add_f32 v[26:27], v[42:43], v[26:27]
	v_mov_b32_e32 v37, s56
	v_pk_add_f32 v[24:25], v[24:25], v[26:27]
	ds_bpermute_b32 v27, v147, v25
	ds_bpermute_b32 v26, v147, v24
	v_or_b32_e32 v36, 16, v10
	v_lshlrev_b64 v[36:37], 11, v[36:37]
	v_or_b32_e32 v10, 24, v10
	v_lshlrev_b64 v[10:11], 11, v[10:11]
	s_waitcnt lgkmcnt(0)
	v_pk_add_f32 v[24:25], v[24:25], v[26:27]
	ds_bpermute_b32 v27, v159, v25
	ds_bpermute_b32 v26, v159, v24
	v_lshl_add_u64 v[10:11], s[74:75], 0, v[10:11]
	v_lshl_add_u64 v[10:11], v[10:11], 0, s[80:81]
	s_waitcnt lgkmcnt(0)
	v_pk_add_f32 v[24:25], v[24:25], v[26:27]
	ds_bpermute_b32 v27, v184, v25
	ds_bpermute_b32 v26, v184, v24
	s_waitcnt lgkmcnt(0)
	v_pk_add_f32 v[24:25], v[24:25], v[26:27]
	s_nop 0
	v_pk_fma_f32 v[12:13], v[24:25], s[2:3], v[12:13] op_sel_hi:[1,0,0]
	v_lshl_add_u64 v[24:25], s[74:75], 0, v[36:37]
	v_mul_f32_e32 v23, 0x4b800000, v13
	v_cmp_gt_f32_e32 vcc, s96, v13
	v_lshl_add_u64 v[24:25], v[24:25], 0, s[80:81]
	v_lshl_add_u64 v[24:25], v[24:25], 0, v[0:1]
	v_cndmask_b32_e32 v13, v13, v23, vcc
	v_rsq_f32_e32 v13, v13
	s_nop 0
	v_mul_f32_e32 v23, 0x45800000, v13
	v_cndmask_b32_e32 v26, v13, v23, vcc
	v_pk_mul_f32 v[34:35], v[26:27], v[34:35] op_sel_hi:[0,1]
	v_pk_mul_f32 v[32:33], v[26:27], v[32:33] op_sel_hi:[0,1]
	v_pk_mul_f32 v[30:31], v[26:27], v[30:31] op_sel_hi:[0,1]
	v_pk_mul_f32 v[26:27], v[26:27], v[28:29] op_sel_hi:[0,1]
	v_mul_f32_e32 v13, 0x4b800000, v12
	v_cmp_gt_f32_e32 vcc, s96, v12
	v_pk_mul_f32 v[28:29], v[68:69], v[30:31]
	v_pk_mul_f32 v[6:7], v[64:65], v[34:35]
	v_pk_mul_f32 v[8:9], v[66:67], v[32:33]
	v_pk_mul_f32 v[26:27], v[70:71], v[26:27]
	v_cvt_pk_bf16_f32 v2, v6, v7
	v_cvt_pk_bf16_f32 v3, v8, v9
	v_cvt_pk_bf16_f32 v4, v28, v29
	v_cvt_pk_bf16_f32 v5, v26, v27
	global_store_dwordx4 v[24:25], v[2:5], off offset:512
	s_nop 0
	v_cndmask_b32_e32 v12, v12, v13, vcc
	v_rsq_f32_e32 v12, v12
	s_nop 0
	v_mul_f32_e32 v13, 0x45800000, v12
	v_cndmask_b32_e32 v12, v12, v13, vcc
	v_pk_mul_f32 v[20:21], v[12:13], v[20:21] op_sel_hi:[0,1]
	v_pk_mul_f32 v[18:19], v[12:13], v[18:19] op_sel_hi:[0,1]
	v_pk_mul_f32 v[16:17], v[12:13], v[16:17] op_sel_hi:[0,1]
	v_pk_mul_f32 v[12:13], v[12:13], v[14:15] op_sel_hi:[0,1]
	v_pk_mul_f32 v[2:3], v[64:65], v[20:21]
	v_pk_mul_f32 v[4:5], v[66:67], v[18:19]
	v_pk_mul_f32 v[6:7], v[68:69], v[16:17]
	v_pk_mul_f32 v[8:9], v[70:71], v[12:13]
	v_cvt_pk_bf16_f32 v2, v2, v3
	v_cvt_pk_bf16_f32 v3, v4, v5
	v_cvt_pk_bf16_f32 v4, v6, v7
	v_cvt_pk_bf16_f32 v5, v8, v9
	v_lshl_add_u64 v[6:7], v[10:11], 0, v[0:1]
	global_store_dwordx4 v[6:7], v[2:5], off offset:512
